# v6 + in-proj epilogue rope tiles: table values loaded once per row group, 3 groups ahead into dead fragment registers, counted vmcnt instead of per-piece vmcnt(0)
# baseline (speedup 1.0000x reference)
.LBB0_686:
	s_lshl_b32 s0, s28, 8
	s_cmp_eq_u32 s28, 6
	s_cselect_b64 vcc, -1, 0
	s_lshl_b32 s4, s26, 8
	v_mov_b32_e32 v148, v160
	s_add_i32 s4, s4, s56
	v_mov_b32_e32 v145, 0x3e000000
	v_add_u32_e32 v162, s4, v148
	v_bitop3_b32 v148, v162, s86, v254 bitop3:0x6c
	v_lshl_add_u32 v144, v144, 3, s57
	v_cndmask_b32_e32 v146, 1.0, v145, vcc
	s_add_i32 s26, s0, 0xfffffd00
	v_cmp_gt_i32_e32 vcc, s86, v162
	v_add_u32_e32 v148, 0x100, v148
	v_lshrrev_b32_e32 v145, 1, v144
	s_ashr_i32 s27, s26, 31
	v_cndmask_b32_sdwa v148, v148, v162, vcc dst_sel:DWORD dst_unused:UNUSED_PAD src0_sel:DWORD src1_sel:BYTE_0
	v_and_b32_e32 v159, 28, v145
	v_ashrrev_i32_e32 v145, 31, v144
	v_lshlrev_b32_e32 v161, 5, v148
	s_cmp_lt_i32 s19, 2
	s_mov_b64 s[28:29], -1
	s_cbranch_scc1 .LBB0_692
	s_cmp_gt_i32 s19, 2
	s_cbranch_scc0 .LBB0_689
	v_add_u32_e32 v220, s4, v160
	v_bitop3_b32 v221, v220, s86, v254 bitop3:0x6c
	v_cmp_gt_i32_e32 vcc, s86, v220
	v_add_u32_e32 v221, 0x100, v221
	v_and_b32_e32 v220, 0xff, v220
	v_cndmask_b32_e32 v221, v221, v220, vcc
	v_lshlrev_b32_e32 v221, 8, v221
	v_lshl_add_u32 v180, v159, 3, v221
	v_lshl_add_u64 v[222:223], s[14:15], 0, v[180:181]
	global_load_dwordx4 v[192:195], v[222:223], off offset:16
	global_load_dwordx4 v[188:191], v[222:223], off
	v_add_u32_e32 v220, s4, v160
	v_add_u32_e32 v220, 0x10, v220
	v_bitop3_b32 v221, v220, s86, v254 bitop3:0x6c
	v_cmp_gt_i32_e32 vcc, s86, v220
	v_add_u32_e32 v221, 0x100, v221
	v_and_b32_e32 v220, 0xff, v220
	v_cndmask_b32_e32 v221, v221, v220, vcc
	v_lshlrev_b32_e32 v221, 8, v221
	v_lshl_add_u32 v180, v159, 3, v221
	v_lshl_add_u64 v[222:223], s[14:15], 0, v[180:181]
	global_load_dwordx4 v[200:203], v[222:223], off offset:16
	global_load_dwordx4 v[196:199], v[222:223], off
	v_add_u32_e32 v220, s4, v160
	v_add_u32_e32 v220, 0x20, v220
	v_bitop3_b32 v221, v220, s86, v254 bitop3:0x6c
	v_cmp_gt_i32_e32 vcc, s86, v220
	v_add_u32_e32 v221, 0x100, v221
	v_and_b32_e32 v220, 0xff, v220
	v_cndmask_b32_e32 v221, v221, v220, vcc
	v_lshlrev_b32_e32 v221, 8, v221
	v_lshl_add_u32 v180, v159, 3, v221
	v_lshl_add_u64 v[222:223], s[14:15], 0, v[180:181]
	global_load_dwordx4 v[208:211], v[222:223], off offset:16
	global_load_dwordx4 v[204:207], v[222:223], off
	s_mov_b64 s[28:29], 0
	s_waitcnt vmcnt(4)
	v_mov_b32_e32 v152, v192
	v_mov_b32_e32 v153, v193
	v_mov_b32_e32 v154, v194
	v_mov_b32_e32 v155, v195
	v_mov_b32_e32 v148, v188
	v_mov_b32_e32 v149, v189
	v_mov_b32_e32 v150, v190
	v_mov_b32_e32 v151, v191
	v_add_u32_e32 v220, s4, v160
	v_add_u32_e32 v220, 0x30, v220
	v_bitop3_b32 v221, v220, s86, v254 bitop3:0x6c
	v_cmp_gt_i32_e32 vcc, s86, v220
	v_add_u32_e32 v221, 0x100, v221
	v_and_b32_e32 v220, 0xff, v220
	v_cndmask_b32_e32 v221, v221, v220, vcc
	v_lshlrev_b32_e32 v221, 8, v221
	v_lshl_add_u32 v180, v159, 3, v221
	v_lshl_add_u64 v[222:223], s[14:15], 0, v[180:181]
	global_load_dwordx4 v[216:219], v[222:223], off offset:16
	global_load_dwordx4 v[212:215], v[222:223], off
	v_pk_mul_f32 v[164:165], v[128:129], v[148:149] op_sel:[1,1] op_sel_hi:[1,0]
	s_nop 0
	v_pk_fma_f32 v[166:167], v[128:129], v[148:149], v[164:165] neg_lo:[0,0,1] neg_hi:[0,0,1]
	v_pk_fma_f32 v[148:149], v[128:129], v[148:149], v[164:165] op_sel_hi:[0,1,1]
	v_mov_b32_e32 v167, v149
	v_pk_mul_f32 v[148:149], v[146:147], v[166:167] op_sel_hi:[0,1]
	v_mul_f32_e32 v164, v131, v151
	v_mul_f32_e32 v166, v130, v151
	v_pk_fma_f32 v[164:165], v[130:131], v[150:151], v[164:165] op_sel_hi:[1,1,0] neg_lo:[0,0,1] neg_hi:[0,0,1]
	v_pk_fma_f32 v[150:151], v[130:131], v[150:151], v[166:167] op_sel:[0,1,0] op_sel_hi:[1,0,0]
	s_nop 0
	v_mov_b32_e32 v165, v151
	v_pk_mul_f32 v[150:151], v[146:147], v[164:165] op_sel_hi:[0,1]
	v_pk_mul_f32 v[164:165], v[124:125], v[152:153] op_sel:[1,1] op_sel_hi:[1,0]
	s_nop 0
	v_pk_fma_f32 v[166:167], v[124:125], v[152:153], v[164:165] neg_lo:[0,0,1] neg_hi:[0,0,1]
	v_pk_fma_f32 v[152:153], v[124:125], v[152:153], v[164:165] op_sel_hi:[0,1,1]
	v_mov_b32_e32 v167, v153
	v_pk_mul_f32 v[152:153], v[146:147], v[166:167] op_sel_hi:[0,1]
	v_mul_f32_e32 v164, v127, v155
	v_mul_f32_e32 v166, v126, v155
	v_pk_fma_f32 v[164:165], v[126:127], v[154:155], v[164:165] op_sel_hi:[1,1,0] neg_lo:[0,0,1] neg_hi:[0,0,1]
	v_pk_fma_f32 v[154:155], v[126:127], v[154:155], v[166:167] op_sel:[0,1,0] op_sel_hi:[1,0,0]
	s_nop 0
	v_mov_b32_e32 v165, v155
	v_pk_mul_f32 v[154:155], v[146:147], v[164:165] op_sel_hi:[0,1]

.LBB0_696:
	v_add_u32_e32 v124, s0, v144
	v_mov_b64_e32 v[126:127], s[12:13]
	v_ashrrev_i32_e32 v125, 31, v124
	v_mad_i64_i32 v[126:127], s[0:1], v162, s2, v[126:127]
	v_lshl_add_u64 v[126:127], v[124:125], 1, v[126:127]
	v_cvt_pk_bf16_f32 v128, v148, v149
	v_cvt_pk_bf16_f32 v129, v150, v151
	v_cvt_pk_bf16_f32 v130, v152, v153
	v_cvt_pk_bf16_f32 v131, v154, v155
	s_cmp_lt_i32 s19, 2
	s_mov_b64 s[28:29], -1
	global_store_dwordx4 v[126:127], v[128:131], off
	s_cbranch_scc1 .LBB0_702
	s_cmp_gt_i32 s19, 2
	s_cbranch_scc0 .LBB0_699
	s_mov_b64 s[28:29], 0
	v_mov_b32_e32 v148, v192
	v_mov_b32_e32 v149, v193
	v_mov_b32_e32 v150, v194
	v_mov_b32_e32 v151, v195
	v_mov_b32_e32 v128, v188
	v_mov_b32_e32 v129, v189
	v_mov_b32_e32 v130, v190
	v_mov_b32_e32 v131, v191
	v_pk_mul_f32 v[152:153], v[120:121], v[128:129] op_sel:[1,1] op_sel_hi:[1,0]
	s_nop 0
	v_pk_fma_f32 v[154:155], v[120:121], v[128:129], v[152:153] neg_lo:[0,0,1] neg_hi:[0,0,1]
	v_pk_fma_f32 v[128:129], v[120:121], v[128:129], v[152:153] op_sel_hi:[0,1,1]
	v_mov_b32_e32 v155, v129
	v_pk_mul_f32 v[128:129], v[146:147], v[154:155] op_sel_hi:[0,1]
	v_mul_f32_e32 v152, v123, v131
	v_mul_f32_e32 v154, v122, v131
	v_pk_fma_f32 v[152:153], v[122:123], v[130:131], v[152:153] op_sel_hi:[1,1,0] neg_lo:[0,0,1] neg_hi:[0,0,1]
	v_pk_fma_f32 v[130:131], v[122:123], v[130:131], v[154:155] op_sel:[0,1,0] op_sel_hi:[1,0,0]
	s_nop 0
	v_mov_b32_e32 v153, v131
	v_pk_mul_f32 v[130:131], v[146:147], v[152:153] op_sel_hi:[0,1]
	v_pk_mul_f32 v[152:153], v[116:117], v[148:149] op_sel:[1,1] op_sel_hi:[1,0]
	s_nop 0
	v_pk_fma_f32 v[154:155], v[116:117], v[148:149], v[152:153] neg_lo:[0,0,1] neg_hi:[0,0,1]
	v_pk_fma_f32 v[148:149], v[116:117], v[148:149], v[152:153] op_sel_hi:[0,1,1]
	v_mov_b32_e32 v155, v149
	v_pk_mul_f32 v[148:149], v[146:147], v[154:155] op_sel_hi:[0,1]
	v_mul_f32_e32 v152, v119, v151
	v_mul_f32_e32 v154, v118, v151
	v_pk_fma_f32 v[152:153], v[118:119], v[150:151], v[152:153] op_sel_hi:[1,1,0] neg_lo:[0,0,1] neg_hi:[0,0,1]
	v_pk_fma_f32 v[150:151], v[118:119], v[150:151], v[154:155] op_sel:[0,1,0] op_sel_hi:[1,0,0]
	s_nop 0
	v_mov_b32_e32 v153, v151
	v_pk_mul_f32 v[150:151], v[146:147], v[152:153] op_sel_hi:[0,1]

.LBB0_706:
	v_cvt_pk_bf16_f32 v116, v128, v129
	v_cvt_pk_bf16_f32 v117, v130, v131
	v_cvt_pk_bf16_f32 v118, v148, v149
	v_cvt_pk_bf16_f32 v119, v150, v151
	global_store_dwordx4 v[126:127], v[116:119], off offset:256
	s_cmp_lt_i32 s19, 2
	s_mov_b64 s[28:29], -1
	v_mov_b32_e32 v116, v160
	s_nop 0
	v_add3_u32 v127, v116, s4, 16
	v_bitop3_b32 v116, v127, s86, v254 bitop3:0x6c
	v_cmp_gt_i32_e32 vcc, s86, v127
	v_add_u32_e32 v116, 0x100, v116
	s_nop 0
	v_cndmask_b32_sdwa v116, v116, v127, vcc dst_sel:DWORD dst_unused:UNUSED_PAD src0_sel:DWORD src1_sel:BYTE_0
	v_lshlrev_b32_e32 v126, 5, v116
	s_cbranch_scc1 .LBB0_712
	s_cmp_gt_i32 s19, 2
	s_cbranch_scc0 .LBB0_709
	s_mov_b64 s[28:29], 0
	s_waitcnt vmcnt(6)
	v_mov_b32_e32 v120, v200
	v_mov_b32_e32 v121, v201
	v_mov_b32_e32 v122, v202
	v_mov_b32_e32 v123, v203
	v_mov_b32_e32 v116, v196
	v_mov_b32_e32 v117, v197
	v_mov_b32_e32 v118, v198
	v_mov_b32_e32 v119, v199
	v_add_u32_e32 v220, s4, v160
	v_add_u32_e32 v220, 0x80, v220
	v_bitop3_b32 v221, v220, s86, v254 bitop3:0x6c
	v_cmp_gt_i32_e32 vcc, s86, v220
	v_add_u32_e32 v221, 0x100, v221
	v_and_b32_e32 v220, 0xff, v220
	v_cndmask_b32_e32 v221, v221, v220, vcc
	v_lshlrev_b32_e32 v221, 8, v221
	v_lshl_add_u32 v180, v159, 3, v221
	v_lshl_add_u64 v[222:223], s[14:15], 0, v[180:181]
	global_load_dwordx4 v[192:195], v[222:223], off offset:16
	global_load_dwordx4 v[188:191], v[222:223], off
	v_pk_mul_f32 v[128:129], v[112:113], v[116:117] op_sel:[1,1] op_sel_hi:[1,0]
	s_nop 0
	v_pk_fma_f32 v[130:131], v[112:113], v[116:117], v[128:129] neg_lo:[0,0,1] neg_hi:[0,0,1]
	v_pk_fma_f32 v[116:117], v[112:113], v[116:117], v[128:129] op_sel_hi:[0,1,1]
	v_mov_b32_e32 v131, v117
	v_pk_mul_f32 v[116:117], v[146:147], v[130:131] op_sel_hi:[0,1]
	v_mul_f32_e32 v128, v115, v119
	v_mul_f32_e32 v130, v114, v119
	v_pk_fma_f32 v[128:129], v[114:115], v[118:119], v[128:129] op_sel_hi:[1,1,0] neg_lo:[0,0,1] neg_hi:[0,0,1]
	v_pk_fma_f32 v[118:119], v[114:115], v[118:119], v[130:131] op_sel:[0,1,0] op_sel_hi:[1,0,0]
	s_nop 0
	v_mov_b32_e32 v129, v119
	v_pk_mul_f32 v[118:119], v[146:147], v[128:129] op_sel_hi:[0,1]
	v_pk_mul_f32 v[128:129], v[108:109], v[120:121] op_sel:[1,1] op_sel_hi:[1,0]
	s_nop 0
	v_pk_fma_f32 v[130:131], v[108:109], v[120:121], v[128:129] neg_lo:[0,0,1] neg_hi:[0,0,1]
	v_pk_fma_f32 v[120:121], v[108:109], v[120:121], v[128:129] op_sel_hi:[0,1,1]
	v_mov_b32_e32 v131, v121
	v_pk_mul_f32 v[120:121], v[146:147], v[130:131] op_sel_hi:[0,1]
	v_mul_f32_e32 v128, v111, v123
	v_mul_f32_e32 v130, v110, v123
	v_pk_fma_f32 v[128:129], v[110:111], v[122:123], v[128:129] op_sel_hi:[1,1,0] neg_lo:[0,0,1] neg_hi:[0,0,1]
	v_pk_fma_f32 v[122:123], v[110:111], v[122:123], v[130:131] op_sel:[0,1,0] op_sel_hi:[1,0,0]
	s_nop 0
	v_mov_b32_e32 v129, v123
	v_pk_mul_f32 v[122:123], v[146:147], v[128:129] op_sel_hi:[0,1]

.LBB0_716:
	v_mov_b64_e32 v[108:109], s[12:13]
	v_mad_i64_i32 v[108:109], s[0:1], v127, s2, v[108:109]
	v_lshl_add_u64 v[108:109], v[124:125], 1, v[108:109]
	v_cvt_pk_bf16_f32 v110, v116, v117
	v_cvt_pk_bf16_f32 v111, v118, v119
	v_cvt_pk_bf16_f32 v112, v120, v121
	v_cvt_pk_bf16_f32 v113, v122, v123
	s_cmp_lt_i32 s19, 2
	s_mov_b64 s[28:29], -1
	global_store_dwordx4 v[108:109], v[110:113], off
	s_cbranch_scc1 .LBB0_722
	s_cmp_gt_i32 s19, 2
	s_cbranch_scc0 .LBB0_719
	s_mov_b64 s[28:29], 0
	v_mov_b32_e32 v114, v200
	v_mov_b32_e32 v115, v201
	v_mov_b32_e32 v116, v202
	v_mov_b32_e32 v117, v203
	v_mov_b32_e32 v110, v196
	v_mov_b32_e32 v111, v197
	v_mov_b32_e32 v112, v198
	v_mov_b32_e32 v113, v199
	v_pk_mul_f32 v[118:119], v[104:105], v[110:111] op_sel:[1,1] op_sel_hi:[1,0]
	s_nop 0
	v_pk_fma_f32 v[120:121], v[104:105], v[110:111], v[118:119] neg_lo:[0,0,1] neg_hi:[0,0,1]
	v_pk_fma_f32 v[110:111], v[104:105], v[110:111], v[118:119] op_sel_hi:[0,1,1]
	v_mov_b32_e32 v121, v111
	v_pk_mul_f32 v[110:111], v[146:147], v[120:121] op_sel_hi:[0,1]
	v_mul_f32_e32 v118, v107, v113
	v_mul_f32_e32 v120, v106, v113
	v_pk_fma_f32 v[118:119], v[106:107], v[112:113], v[118:119] op_sel_hi:[1,1,0] neg_lo:[0,0,1] neg_hi:[0,0,1]
	v_pk_fma_f32 v[112:113], v[106:107], v[112:113], v[120:121] op_sel:[0,1,0] op_sel_hi:[1,0,0]
	s_nop 0
	v_mov_b32_e32 v119, v113
	v_pk_mul_f32 v[112:113], v[146:147], v[118:119] op_sel_hi:[0,1]
	v_pk_mul_f32 v[118:119], v[100:101], v[114:115] op_sel:[1,1] op_sel_hi:[1,0]
	s_nop 0
	v_pk_fma_f32 v[120:121], v[100:101], v[114:115], v[118:119] neg_lo:[0,0,1] neg_hi:[0,0,1]
	v_pk_fma_f32 v[114:115], v[100:101], v[114:115], v[118:119] op_sel_hi:[0,1,1]
	v_mov_b32_e32 v121, v115
	v_pk_mul_f32 v[114:115], v[146:147], v[120:121] op_sel_hi:[0,1]
	v_mul_f32_e32 v118, v103, v117
	v_mul_f32_e32 v120, v102, v117
	v_pk_fma_f32 v[118:119], v[102:103], v[116:117], v[118:119] op_sel_hi:[1,1,0] neg_lo:[0,0,1] neg_hi:[0,0,1]
	v_pk_fma_f32 v[116:117], v[102:103], v[116:117], v[120:121] op_sel:[0,1,0] op_sel_hi:[1,0,0]
	s_nop 0
	v_mov_b32_e32 v119, v117
	v_pk_mul_f32 v[116:117], v[146:147], v[118:119] op_sel_hi:[0,1]

.LBB0_726:
	v_cvt_pk_bf16_f32 v100, v110, v111
	v_cvt_pk_bf16_f32 v101, v112, v113
	v_cvt_pk_bf16_f32 v102, v114, v115
	v_cvt_pk_bf16_f32 v103, v116, v117
	global_store_dwordx4 v[108:109], v[100:103], off offset:256
	s_cmp_lt_i32 s19, 2
	s_mov_b64 s[28:29], -1
	v_mov_b32_e32 v100, v160
	s_nop 0
	v_add3_u32 v109, v100, s4, 32
	v_bitop3_b32 v100, v109, s86, v254 bitop3:0x6c
	v_cmp_gt_i32_e32 vcc, s86, v109
	v_add_u32_e32 v100, 0x100, v100
	s_nop 0
	v_cndmask_b32_sdwa v100, v100, v109, vcc dst_sel:DWORD dst_unused:UNUSED_PAD src0_sel:DWORD src1_sel:BYTE_0
	v_lshlrev_b32_e32 v108, 5, v100
	s_cbranch_scc1 .LBB0_732
	s_cmp_gt_i32 s19, 2
	s_cbranch_scc0 .LBB0_729
	s_mov_b64 s[28:29], 0
	s_waitcnt vmcnt(8)
	v_mov_b32_e32 v104, v208
	v_mov_b32_e32 v105, v209
	v_mov_b32_e32 v106, v210
	v_mov_b32_e32 v107, v211
	v_mov_b32_e32 v100, v204
	v_mov_b32_e32 v101, v205
	v_mov_b32_e32 v102, v206
	v_mov_b32_e32 v103, v207
	v_add_u32_e32 v220, s4, v160
	v_add_u32_e32 v220, 0x90, v220
	v_bitop3_b32 v221, v220, s86, v254 bitop3:0x6c
	v_cmp_gt_i32_e32 vcc, s86, v220
	v_add_u32_e32 v221, 0x100, v221
	v_and_b32_e32 v220, 0xff, v220
	v_cndmask_b32_e32 v221, v221, v220, vcc
	v_lshlrev_b32_e32 v221, 8, v221
	v_lshl_add_u32 v180, v159, 3, v221
	v_lshl_add_u64 v[222:223], s[14:15], 0, v[180:181]
	global_load_dwordx4 v[200:203], v[222:223], off offset:16
	global_load_dwordx4 v[196:199], v[222:223], off
	v_pk_mul_f32 v[110:111], v[96:97], v[100:101] op_sel:[1,1] op_sel_hi:[1,0]
	s_nop 0
	v_pk_fma_f32 v[112:113], v[96:97], v[100:101], v[110:111] neg_lo:[0,0,1] neg_hi:[0,0,1]
	v_pk_fma_f32 v[100:101], v[96:97], v[100:101], v[110:111] op_sel_hi:[0,1,1]
	v_mov_b32_e32 v113, v101
	v_pk_mul_f32 v[100:101], v[146:147], v[112:113] op_sel_hi:[0,1]
	v_mul_f32_e32 v110, v99, v103
	v_mul_f32_e32 v112, v98, v103
	v_pk_fma_f32 v[110:111], v[98:99], v[102:103], v[110:111] op_sel_hi:[1,1,0] neg_lo:[0,0,1] neg_hi:[0,0,1]
	v_pk_fma_f32 v[102:103], v[98:99], v[102:103], v[112:113] op_sel:[0,1,0] op_sel_hi:[1,0,0]
	s_nop 0
	v_mov_b32_e32 v111, v103
	v_pk_mul_f32 v[102:103], v[146:147], v[110:111] op_sel_hi:[0,1]
	v_pk_mul_f32 v[110:111], v[92:93], v[104:105] op_sel:[1,1] op_sel_hi:[1,0]
	s_nop 0
	v_pk_fma_f32 v[112:113], v[92:93], v[104:105], v[110:111] neg_lo:[0,0,1] neg_hi:[0,0,1]
	v_pk_fma_f32 v[104:105], v[92:93], v[104:105], v[110:111] op_sel_hi:[0,1,1]
	v_mov_b32_e32 v113, v105
	v_pk_mul_f32 v[104:105], v[146:147], v[112:113] op_sel_hi:[0,1]
	v_mul_f32_e32 v110, v95, v107
	v_mul_f32_e32 v112, v94, v107
	v_pk_fma_f32 v[110:111], v[94:95], v[106:107], v[110:111] op_sel_hi:[1,1,0] neg_lo:[0,0,1] neg_hi:[0,0,1]
	v_pk_fma_f32 v[106:107], v[94:95], v[106:107], v[112:113] op_sel:[0,1,0] op_sel_hi:[1,0,0]
	s_nop 0
	v_mov_b32_e32 v111, v107
	v_pk_mul_f32 v[106:107], v[146:147], v[110:111] op_sel_hi:[0,1]

.LBB0_736:
	v_mov_b64_e32 v[92:93], s[12:13]
	v_mad_i64_i32 v[92:93], s[0:1], v109, s2, v[92:93]
	v_lshl_add_u64 v[92:93], v[124:125], 1, v[92:93]
	v_cvt_pk_bf16_f32 v94, v100, v101
	v_cvt_pk_bf16_f32 v95, v102, v103
	v_cvt_pk_bf16_f32 v96, v104, v105
	v_cvt_pk_bf16_f32 v97, v106, v107
	s_cmp_lt_i32 s19, 2
	s_mov_b64 s[28:29], -1
	global_store_dwordx4 v[92:93], v[94:97], off
	s_cbranch_scc1 .LBB0_742
	s_cmp_gt_i32 s19, 2
	s_cbranch_scc0 .LBB0_739
	s_mov_b64 s[28:29], 0
	v_mov_b32_e32 v98, v208
	v_mov_b32_e32 v99, v209
	v_mov_b32_e32 v100, v210
	v_mov_b32_e32 v101, v211
	v_mov_b32_e32 v94, v204
	v_mov_b32_e32 v95, v205
	v_mov_b32_e32 v96, v206
	v_mov_b32_e32 v97, v207
	v_pk_mul_f32 v[102:103], v[88:89], v[94:95] op_sel:[1,1] op_sel_hi:[1,0]
	s_nop 0
	v_pk_fma_f32 v[104:105], v[88:89], v[94:95], v[102:103] neg_lo:[0,0,1] neg_hi:[0,0,1]
	v_pk_fma_f32 v[94:95], v[88:89], v[94:95], v[102:103] op_sel_hi:[0,1,1]
	v_mov_b32_e32 v105, v95
	v_pk_mul_f32 v[94:95], v[146:147], v[104:105] op_sel_hi:[0,1]
	v_mul_f32_e32 v102, v91, v97
	v_mul_f32_e32 v104, v90, v97
	v_pk_fma_f32 v[102:103], v[90:91], v[96:97], v[102:103] op_sel_hi:[1,1,0] neg_lo:[0,0,1] neg_hi:[0,0,1]
	v_pk_fma_f32 v[96:97], v[90:91], v[96:97], v[104:105] op_sel:[0,1,0] op_sel_hi:[1,0,0]
	s_nop 0
	v_mov_b32_e32 v103, v97
	v_pk_mul_f32 v[96:97], v[146:147], v[102:103] op_sel_hi:[0,1]
	v_pk_mul_f32 v[102:103], v[84:85], v[98:99] op_sel:[1,1] op_sel_hi:[1,0]
	s_nop 0
	v_pk_fma_f32 v[104:105], v[84:85], v[98:99], v[102:103] neg_lo:[0,0,1] neg_hi:[0,0,1]
	v_pk_fma_f32 v[98:99], v[84:85], v[98:99], v[102:103] op_sel_hi:[0,1,1]
	v_mov_b32_e32 v105, v99
	v_pk_mul_f32 v[98:99], v[146:147], v[104:105] op_sel_hi:[0,1]
	v_mul_f32_e32 v102, v87, v101
	v_mul_f32_e32 v104, v86, v101
	v_pk_fma_f32 v[102:103], v[86:87], v[100:101], v[102:103] op_sel_hi:[1,1,0] neg_lo:[0,0,1] neg_hi:[0,0,1]
	v_pk_fma_f32 v[100:101], v[86:87], v[100:101], v[104:105] op_sel:[0,1,0] op_sel_hi:[1,0,0]
	s_nop 0
	v_mov_b32_e32 v103, v101
	v_pk_mul_f32 v[100:101], v[146:147], v[102:103] op_sel_hi:[0,1]

.LBB0_746:
	v_cvt_pk_bf16_f32 v84, v94, v95
	v_cvt_pk_bf16_f32 v85, v96, v97
	v_cvt_pk_bf16_f32 v86, v98, v99
	v_cvt_pk_bf16_f32 v87, v100, v101
	global_store_dwordx4 v[92:93], v[84:87], off offset:256
	s_cmp_lt_i32 s19, 2
	s_mov_b64 s[28:29], -1
	v_mov_b32_e32 v84, v160
	s_nop 0
	v_add3_u32 v84, v84, s4, 48
	v_bitop3_b32 v85, v84, s86, v254 bitop3:0x6c
	v_cmp_gt_i32_e32 vcc, s86, v84
	v_add_u32_e32 v85, 0x100, v85
	s_nop 0
	v_cndmask_b32_sdwa v85, v85, v84, vcc dst_sel:DWORD dst_unused:UNUSED_PAD src0_sel:DWORD src1_sel:BYTE_0
	v_lshlrev_b32_e32 v94, 5, v85
	s_cbranch_scc1 .LBB0_752
	s_cmp_gt_i32 s19, 2
	s_cbranch_scc0 .LBB0_749
	s_mov_b64 s[28:29], 0
	s_waitcnt vmcnt(10)
	v_mov_b32_e32 v90, v216
	v_mov_b32_e32 v91, v217
	v_mov_b32_e32 v92, v218
	v_mov_b32_e32 v93, v219
	v_mov_b32_e32 v86, v212
	v_mov_b32_e32 v87, v213
	v_mov_b32_e32 v88, v214
	v_mov_b32_e32 v89, v215
	v_add_u32_e32 v220, s4, v160
	v_add_u32_e32 v220, 0xa0, v220
	v_bitop3_b32 v221, v220, s86, v254 bitop3:0x6c
	v_cmp_gt_i32_e32 vcc, s86, v220
	v_add_u32_e32 v221, 0x100, v221
	v_and_b32_e32 v220, 0xff, v220
	v_cndmask_b32_e32 v221, v221, v220, vcc
	v_lshlrev_b32_e32 v221, 8, v221
	v_lshl_add_u32 v180, v159, 3, v221
	v_lshl_add_u64 v[222:223], s[14:15], 0, v[180:181]
	global_load_dwordx4 v[208:211], v[222:223], off offset:16
	global_load_dwordx4 v[204:207], v[222:223], off
	v_pk_mul_f32 v[96:97], v[80:81], v[86:87] op_sel:[1,1] op_sel_hi:[1,0]
	s_nop 0
	v_pk_fma_f32 v[98:99], v[80:81], v[86:87], v[96:97] neg_lo:[0,0,1] neg_hi:[0,0,1]
	v_pk_fma_f32 v[86:87], v[80:81], v[86:87], v[96:97] op_sel_hi:[0,1,1]
	v_mov_b32_e32 v99, v87
	v_pk_mul_f32 v[86:87], v[146:147], v[98:99] op_sel_hi:[0,1]
	v_mul_f32_e32 v96, v83, v89
	v_mul_f32_e32 v98, v82, v89
	v_pk_fma_f32 v[96:97], v[82:83], v[88:89], v[96:97] op_sel_hi:[1,1,0] neg_lo:[0,0,1] neg_hi:[0,0,1]
	v_pk_fma_f32 v[88:89], v[82:83], v[88:89], v[98:99] op_sel:[0,1,0] op_sel_hi:[1,0,0]
	s_nop 0
	v_mov_b32_e32 v97, v89
	v_pk_mul_f32 v[88:89], v[146:147], v[96:97] op_sel_hi:[0,1]
	v_pk_mul_f32 v[96:97], v[76:77], v[90:91] op_sel:[1,1] op_sel_hi:[1,0]
	s_nop 0
	v_pk_fma_f32 v[98:99], v[76:77], v[90:91], v[96:97] neg_lo:[0,0,1] neg_hi:[0,0,1]
	v_pk_fma_f32 v[90:91], v[76:77], v[90:91], v[96:97] op_sel_hi:[0,1,1]
	v_mov_b32_e32 v99, v91
	v_pk_mul_f32 v[90:91], v[146:147], v[98:99] op_sel_hi:[0,1]
	v_mul_f32_e32 v96, v79, v93
	v_mul_f32_e32 v98, v78, v93
	v_pk_fma_f32 v[96:97], v[78:79], v[92:93], v[96:97] op_sel_hi:[1,1,0] neg_lo:[0,0,1] neg_hi:[0,0,1]
	v_pk_fma_f32 v[92:93], v[78:79], v[92:93], v[98:99] op_sel:[0,1,0] op_sel_hi:[1,0,0]
	s_nop 0
	v_mov_b32_e32 v97, v93
	v_pk_mul_f32 v[92:93], v[146:147], v[96:97] op_sel_hi:[0,1]

.LBB0_756:
	v_mov_b64_e32 v[76:77], s[12:13]
	v_mad_i64_i32 v[76:77], s[0:1], v84, s2, v[76:77]
	v_lshl_add_u64 v[84:85], v[124:125], 1, v[76:77]
	v_cvt_pk_bf16_f32 v76, v86, v87
	v_cvt_pk_bf16_f32 v77, v88, v89
	v_cvt_pk_bf16_f32 v78, v90, v91
	v_cvt_pk_bf16_f32 v79, v92, v93
	s_cmp_lt_i32 s19, 2
	s_mov_b64 s[28:29], -1
	global_store_dwordx4 v[84:85], v[76:79], off
	s_cbranch_scc1 .LBB0_762
	s_cmp_gt_i32 s19, 2
	s_cbranch_scc0 .LBB0_759
	s_mov_b64 s[28:29], 0
	v_mov_b32_e32 v80, v216
	v_mov_b32_e32 v81, v217
	v_mov_b32_e32 v82, v218
	v_mov_b32_e32 v83, v219
	v_mov_b32_e32 v76, v212
	v_mov_b32_e32 v77, v213
	v_mov_b32_e32 v78, v214
	v_mov_b32_e32 v79, v215
	v_pk_mul_f32 v[86:87], v[72:73], v[76:77] op_sel:[1,1] op_sel_hi:[1,0]
	s_nop 0
	v_pk_fma_f32 v[88:89], v[72:73], v[76:77], v[86:87] neg_lo:[0,0,1] neg_hi:[0,0,1]
	v_pk_fma_f32 v[76:77], v[72:73], v[76:77], v[86:87] op_sel_hi:[0,1,1]
	v_mov_b32_e32 v89, v77
	v_pk_mul_f32 v[76:77], v[146:147], v[88:89] op_sel_hi:[0,1]
	v_mul_f32_e32 v86, v75, v79
	v_mul_f32_e32 v88, v74, v79
	v_pk_fma_f32 v[86:87], v[74:75], v[78:79], v[86:87] op_sel_hi:[1,1,0] neg_lo:[0,0,1] neg_hi:[0,0,1]
	v_pk_fma_f32 v[78:79], v[74:75], v[78:79], v[88:89] op_sel:[0,1,0] op_sel_hi:[1,0,0]
	s_nop 0
	v_mov_b32_e32 v87, v79
	v_pk_mul_f32 v[78:79], v[146:147], v[86:87] op_sel_hi:[0,1]
	v_pk_mul_f32 v[86:87], v[68:69], v[80:81] op_sel:[1,1] op_sel_hi:[1,0]
	s_nop 0
	v_pk_fma_f32 v[88:89], v[68:69], v[80:81], v[86:87] neg_lo:[0,0,1] neg_hi:[0,0,1]
	v_pk_fma_f32 v[80:81], v[68:69], v[80:81], v[86:87] op_sel_hi:[0,1,1]
	v_mov_b32_e32 v89, v81
	v_pk_mul_f32 v[80:81], v[146:147], v[88:89] op_sel_hi:[0,1]
	v_mul_f32_e32 v86, v71, v83
	v_mul_f32_e32 v88, v70, v83
	v_pk_fma_f32 v[86:87], v[70:71], v[82:83], v[86:87] op_sel_hi:[1,1,0] neg_lo:[0,0,1] neg_hi:[0,0,1]
	v_pk_fma_f32 v[82:83], v[70:71], v[82:83], v[88:89] op_sel:[0,1,0] op_sel_hi:[1,0,0]
	s_nop 0
	v_mov_b32_e32 v87, v83
	v_pk_mul_f32 v[82:83], v[146:147], v[86:87] op_sel_hi:[0,1]

.LBB0_766:
	v_cvt_pk_bf16_f32 v68, v76, v77
	v_cvt_pk_bf16_f32 v69, v78, v79
	v_cvt_pk_bf16_f32 v70, v80, v81
	v_cvt_pk_bf16_f32 v71, v82, v83
	global_store_dwordx4 v[84:85], v[68:71], off offset:256
	s_add_i32 s0, s4, 0x80
	s_cmp_lt_i32 s19, 2
	v_mov_b32_e32 v68, v160
	s_mov_b64 s[28:29], -1
	v_add_u32_e32 v77, s0, v68
	v_bitop3_b32 v68, v77, s86, v254 bitop3:0x6c
	v_cmp_gt_i32_e32 vcc, s86, v77
	v_add_u32_e32 v68, 0x100, v68
	s_nop 0
	v_cndmask_b32_sdwa v68, v68, v77, vcc dst_sel:DWORD dst_unused:UNUSED_PAD src0_sel:DWORD src1_sel:BYTE_0
	v_lshlrev_b32_e32 v76, 5, v68
	s_cbranch_scc1 .LBB0_772
	s_cmp_gt_i32 s19, 2
	s_cbranch_scc0 .LBB0_769
	s_mov_b64 s[28:29], 0
	s_waitcnt vmcnt(10)
	v_mov_b32_e32 v72, v192
	v_mov_b32_e32 v73, v193
	v_mov_b32_e32 v74, v194
	v_mov_b32_e32 v75, v195
	v_mov_b32_e32 v68, v188
	v_mov_b32_e32 v69, v189
	v_mov_b32_e32 v70, v190
	v_mov_b32_e32 v71, v191
	v_add_u32_e32 v220, s4, v160
	v_add_u32_e32 v220, 0xb0, v220
	v_bitop3_b32 v221, v220, s86, v254 bitop3:0x6c
	v_cmp_gt_i32_e32 vcc, s86, v220
	v_add_u32_e32 v221, 0x100, v221
	v_and_b32_e32 v220, 0xff, v220
	v_cndmask_b32_e32 v221, v221, v220, vcc
	v_lshlrev_b32_e32 v221, 8, v221
	v_lshl_add_u32 v180, v159, 3, v221
	v_lshl_add_u64 v[222:223], s[14:15], 0, v[180:181]
	global_load_dwordx4 v[216:219], v[222:223], off offset:16
	global_load_dwordx4 v[212:215], v[222:223], off
	v_pk_mul_f32 v[78:79], v[64:65], v[68:69] op_sel:[1,1] op_sel_hi:[1,0]
	s_nop 0
	v_pk_fma_f32 v[80:81], v[64:65], v[68:69], v[78:79] neg_lo:[0,0,1] neg_hi:[0,0,1]
	v_pk_fma_f32 v[68:69], v[64:65], v[68:69], v[78:79] op_sel_hi:[0,1,1]
	v_mov_b32_e32 v81, v69
	v_pk_mul_f32 v[68:69], v[146:147], v[80:81] op_sel_hi:[0,1]
	v_mul_f32_e32 v78, v67, v71
	v_mul_f32_e32 v80, v66, v71
	v_pk_fma_f32 v[78:79], v[66:67], v[70:71], v[78:79] op_sel_hi:[1,1,0] neg_lo:[0,0,1] neg_hi:[0,0,1]
	v_pk_fma_f32 v[70:71], v[66:67], v[70:71], v[80:81] op_sel:[0,1,0] op_sel_hi:[1,0,0]
	s_nop 0
	v_mov_b32_e32 v79, v71
	v_pk_mul_f32 v[70:71], v[146:147], v[78:79] op_sel_hi:[0,1]
	v_pk_mul_f32 v[78:79], v[60:61], v[72:73] op_sel:[1,1] op_sel_hi:[1,0]
	s_nop 0
	v_pk_fma_f32 v[80:81], v[60:61], v[72:73], v[78:79] neg_lo:[0,0,1] neg_hi:[0,0,1]
	v_pk_fma_f32 v[72:73], v[60:61], v[72:73], v[78:79] op_sel_hi:[0,1,1]
	v_mov_b32_e32 v81, v73
	v_pk_mul_f32 v[72:73], v[146:147], v[80:81] op_sel_hi:[0,1]
	v_mul_f32_e32 v78, v63, v75
	v_mul_f32_e32 v80, v62, v75
	v_pk_fma_f32 v[78:79], v[62:63], v[74:75], v[78:79] op_sel_hi:[1,1,0] neg_lo:[0,0,1] neg_hi:[0,0,1]
	v_pk_fma_f32 v[74:75], v[62:63], v[74:75], v[80:81] op_sel:[0,1,0] op_sel_hi:[1,0,0]
	s_nop 0
	v_mov_b32_e32 v79, v75
	v_pk_mul_f32 v[74:75], v[146:147], v[78:79] op_sel_hi:[0,1]

.LBB0_776:
	v_mov_b64_e32 v[60:61], s[12:13]
	v_mad_i64_i32 v[60:61], s[0:1], v77, s2, v[60:61]
	v_lshl_add_u64 v[60:61], v[124:125], 1, v[60:61]
	v_cvt_pk_bf16_f32 v62, v68, v69
	v_cvt_pk_bf16_f32 v63, v70, v71
	v_cvt_pk_bf16_f32 v64, v72, v73
	v_cvt_pk_bf16_f32 v65, v74, v75
	s_cmp_lt_i32 s19, 2
	s_mov_b64 s[28:29], -1
	global_store_dwordx4 v[60:61], v[62:65], off
	s_cbranch_scc1 .LBB0_782
	s_cmp_gt_i32 s19, 2
	s_cbranch_scc0 .LBB0_779
	s_mov_b64 s[28:29], 0
	v_mov_b32_e32 v66, v192
	v_mov_b32_e32 v67, v193
	v_mov_b32_e32 v68, v194
	v_mov_b32_e32 v69, v195
	v_mov_b32_e32 v62, v188
	v_mov_b32_e32 v63, v189
	v_mov_b32_e32 v64, v190
	v_mov_b32_e32 v65, v191
	v_pk_mul_f32 v[70:71], v[56:57], v[62:63] op_sel:[1,1] op_sel_hi:[1,0]
	s_nop 0
	v_pk_fma_f32 v[72:73], v[56:57], v[62:63], v[70:71] neg_lo:[0,0,1] neg_hi:[0,0,1]
	v_pk_fma_f32 v[62:63], v[56:57], v[62:63], v[70:71] op_sel_hi:[0,1,1]
	v_mov_b32_e32 v73, v63
	v_pk_mul_f32 v[62:63], v[146:147], v[72:73] op_sel_hi:[0,1]
	v_mul_f32_e32 v70, v59, v65
	v_mul_f32_e32 v72, v58, v65
	v_pk_fma_f32 v[70:71], v[58:59], v[64:65], v[70:71] op_sel_hi:[1,1,0] neg_lo:[0,0,1] neg_hi:[0,0,1]
	v_pk_fma_f32 v[64:65], v[58:59], v[64:65], v[72:73] op_sel:[0,1,0] op_sel_hi:[1,0,0]
	s_nop 0
	v_mov_b32_e32 v71, v65
	v_pk_mul_f32 v[64:65], v[146:147], v[70:71] op_sel_hi:[0,1]
	v_pk_mul_f32 v[70:71], v[52:53], v[66:67] op_sel:[1,1] op_sel_hi:[1,0]
	s_nop 0
	v_pk_fma_f32 v[72:73], v[52:53], v[66:67], v[70:71] neg_lo:[0,0,1] neg_hi:[0,0,1]
	v_pk_fma_f32 v[66:67], v[52:53], v[66:67], v[70:71] op_sel_hi:[0,1,1]
	v_mov_b32_e32 v73, v67
	v_pk_mul_f32 v[66:67], v[146:147], v[72:73] op_sel_hi:[0,1]
	v_mul_f32_e32 v70, v55, v69
	v_mul_f32_e32 v72, v54, v69
	v_pk_fma_f32 v[70:71], v[54:55], v[68:69], v[70:71] op_sel_hi:[1,1,0] neg_lo:[0,0,1] neg_hi:[0,0,1]
	v_pk_fma_f32 v[68:69], v[54:55], v[68:69], v[72:73] op_sel:[0,1,0] op_sel_hi:[1,0,0]
	s_nop 0
	v_mov_b32_e32 v71, v69
	v_pk_mul_f32 v[68:69], v[146:147], v[70:71] op_sel_hi:[0,1]

.LBB0_786:
	v_cvt_pk_bf16_f32 v52, v62, v63
	v_cvt_pk_bf16_f32 v53, v64, v65
	v_cvt_pk_bf16_f32 v54, v66, v67
	v_cvt_pk_bf16_f32 v55, v68, v69
	global_store_dwordx4 v[60:61], v[52:55], off offset:256
	s_add_i32 s0, s4, 0x90
	s_cmp_lt_i32 s19, 2
	v_mov_b32_e32 v52, v160
	s_mov_b64 s[28:29], -1
	v_add_u32_e32 v61, s0, v52
	v_bitop3_b32 v52, v61, s86, v254 bitop3:0x6c
	v_cmp_gt_i32_e32 vcc, s86, v61
	v_add_u32_e32 v52, 0x100, v52
	s_nop 0
	v_cndmask_b32_sdwa v52, v52, v61, vcc dst_sel:DWORD dst_unused:UNUSED_PAD src0_sel:DWORD src1_sel:BYTE_0
	v_lshlrev_b32_e32 v60, 5, v52
	s_cbranch_scc1 .LBB0_792
	s_cmp_gt_i32 s19, 2
	s_cbranch_scc0 .LBB0_789
	s_mov_b64 s[28:29], 0
	s_waitcnt vmcnt(10)
	v_mov_b32_e32 v56, v200
	v_mov_b32_e32 v57, v201
	v_mov_b32_e32 v58, v202
	v_mov_b32_e32 v59, v203
	v_mov_b32_e32 v52, v196
	v_mov_b32_e32 v53, v197
	v_mov_b32_e32 v54, v198
	v_mov_b32_e32 v55, v199
	v_pk_mul_f32 v[62:63], v[48:49], v[52:53] op_sel:[1,1] op_sel_hi:[1,0]
	s_nop 0
	v_pk_fma_f32 v[64:65], v[48:49], v[52:53], v[62:63] neg_lo:[0,0,1] neg_hi:[0,0,1]
	v_pk_fma_f32 v[52:53], v[48:49], v[52:53], v[62:63] op_sel_hi:[0,1,1]
	v_mov_b32_e32 v65, v53
	v_pk_mul_f32 v[52:53], v[146:147], v[64:65] op_sel_hi:[0,1]
	v_mul_f32_e32 v62, v51, v55
	v_mul_f32_e32 v64, v50, v55
	v_pk_fma_f32 v[62:63], v[50:51], v[54:55], v[62:63] op_sel_hi:[1,1,0] neg_lo:[0,0,1] neg_hi:[0,0,1]
	v_pk_fma_f32 v[54:55], v[50:51], v[54:55], v[64:65] op_sel:[0,1,0] op_sel_hi:[1,0,0]
	s_nop 0
	v_mov_b32_e32 v63, v55
	v_pk_mul_f32 v[54:55], v[146:147], v[62:63] op_sel_hi:[0,1]
	v_pk_mul_f32 v[62:63], v[44:45], v[56:57] op_sel:[1,1] op_sel_hi:[1,0]
	s_nop 0
	v_pk_fma_f32 v[64:65], v[44:45], v[56:57], v[62:63] neg_lo:[0,0,1] neg_hi:[0,0,1]
	v_pk_fma_f32 v[56:57], v[44:45], v[56:57], v[62:63] op_sel_hi:[0,1,1]
	v_mov_b32_e32 v65, v57
	v_pk_mul_f32 v[56:57], v[146:147], v[64:65] op_sel_hi:[0,1]
	v_mul_f32_e32 v62, v47, v59
	v_mul_f32_e32 v64, v46, v59
	v_pk_fma_f32 v[62:63], v[46:47], v[58:59], v[62:63] op_sel_hi:[1,1,0] neg_lo:[0,0,1] neg_hi:[0,0,1]
	v_pk_fma_f32 v[58:59], v[46:47], v[58:59], v[64:65] op_sel:[0,1,0] op_sel_hi:[1,0,0]
	s_nop 0
	v_mov_b32_e32 v63, v59
	v_pk_mul_f32 v[58:59], v[146:147], v[62:63] op_sel_hi:[0,1]

.LBB0_796:
	v_mov_b64_e32 v[44:45], s[12:13]
	v_mad_i64_i32 v[44:45], s[0:1], v61, s2, v[44:45]
	v_lshl_add_u64 v[44:45], v[124:125], 1, v[44:45]
	v_cvt_pk_bf16_f32 v46, v52, v53
	v_cvt_pk_bf16_f32 v47, v54, v55
	v_cvt_pk_bf16_f32 v48, v56, v57
	v_cvt_pk_bf16_f32 v49, v58, v59
	s_cmp_lt_i32 s19, 2
	s_mov_b64 s[28:29], -1
	global_store_dwordx4 v[44:45], v[46:49], off
	s_cbranch_scc1 .LBB0_802
	s_cmp_gt_i32 s19, 2
	s_cbranch_scc0 .LBB0_799
	s_mov_b64 s[28:29], 0
	v_mov_b32_e32 v50, v200
	v_mov_b32_e32 v51, v201
	v_mov_b32_e32 v52, v202
	v_mov_b32_e32 v53, v203
	v_mov_b32_e32 v46, v196
	v_mov_b32_e32 v47, v197
	v_mov_b32_e32 v48, v198
	v_mov_b32_e32 v49, v199
	v_pk_mul_f32 v[54:55], v[40:41], v[46:47] op_sel:[1,1] op_sel_hi:[1,0]
	s_nop 0
	v_pk_fma_f32 v[56:57], v[40:41], v[46:47], v[54:55] neg_lo:[0,0,1] neg_hi:[0,0,1]
	v_pk_fma_f32 v[46:47], v[40:41], v[46:47], v[54:55] op_sel_hi:[0,1,1]
	v_mov_b32_e32 v57, v47
	v_pk_mul_f32 v[46:47], v[146:147], v[56:57] op_sel_hi:[0,1]
	v_mul_f32_e32 v54, v43, v49
	v_mul_f32_e32 v56, v42, v49
	v_pk_fma_f32 v[54:55], v[42:43], v[48:49], v[54:55] op_sel_hi:[1,1,0] neg_lo:[0,0,1] neg_hi:[0,0,1]
	v_pk_fma_f32 v[48:49], v[42:43], v[48:49], v[56:57] op_sel:[0,1,0] op_sel_hi:[1,0,0]
	s_nop 0
	v_mov_b32_e32 v55, v49
	v_pk_mul_f32 v[48:49], v[146:147], v[54:55] op_sel_hi:[0,1]
	v_pk_mul_f32 v[54:55], v[36:37], v[50:51] op_sel:[1,1] op_sel_hi:[1,0]
	s_nop 0
	v_pk_fma_f32 v[56:57], v[36:37], v[50:51], v[54:55] neg_lo:[0,0,1] neg_hi:[0,0,1]
	v_pk_fma_f32 v[50:51], v[36:37], v[50:51], v[54:55] op_sel_hi:[0,1,1]
	v_mov_b32_e32 v57, v51
	v_pk_mul_f32 v[50:51], v[146:147], v[56:57] op_sel_hi:[0,1]
	v_mul_f32_e32 v54, v39, v53
	v_mul_f32_e32 v56, v38, v53
	v_pk_fma_f32 v[54:55], v[38:39], v[52:53], v[54:55] op_sel_hi:[1,1,0] neg_lo:[0,0,1] neg_hi:[0,0,1]
	v_pk_fma_f32 v[52:53], v[38:39], v[52:53], v[56:57] op_sel:[0,1,0] op_sel_hi:[1,0,0]
	s_nop 0
	v_mov_b32_e32 v55, v53
	v_pk_mul_f32 v[52:53], v[146:147], v[54:55] op_sel_hi:[0,1]

.LBB0_806:
	v_cvt_pk_bf16_f32 v36, v46, v47
	v_cvt_pk_bf16_f32 v37, v48, v49
	v_cvt_pk_bf16_f32 v38, v50, v51
	v_cvt_pk_bf16_f32 v39, v52, v53
	global_store_dwordx4 v[44:45], v[36:39], off offset:256
	s_add_i32 s0, s4, 0xa0
	s_cmp_lt_i32 s19, 2
	v_mov_b32_e32 v36, v160
	s_mov_b64 s[28:29], -1
	v_add_u32_e32 v45, s0, v36
	v_bitop3_b32 v36, v45, s86, v254 bitop3:0x6c
	v_cmp_gt_i32_e32 vcc, s86, v45
	v_add_u32_e32 v36, 0x100, v36
	s_nop 0
	v_cndmask_b32_sdwa v36, v36, v45, vcc dst_sel:DWORD dst_unused:UNUSED_PAD src0_sel:DWORD src1_sel:BYTE_0
	v_lshlrev_b32_e32 v44, 5, v36
	s_cbranch_scc1 .LBB0_812
	s_cmp_gt_i32 s19, 2
	s_cbranch_scc0 .LBB0_809
	s_mov_b64 s[28:29], 0
	s_waitcnt vmcnt(8)
	v_mov_b32_e32 v40, v208
	v_mov_b32_e32 v41, v209
	v_mov_b32_e32 v42, v210
	v_mov_b32_e32 v43, v211
	v_mov_b32_e32 v36, v204
	v_mov_b32_e32 v37, v205
	v_mov_b32_e32 v38, v206
	v_mov_b32_e32 v39, v207
	v_pk_mul_f32 v[46:47], v[32:33], v[36:37] op_sel:[1,1] op_sel_hi:[1,0]
	s_nop 0
	v_pk_fma_f32 v[48:49], v[32:33], v[36:37], v[46:47] neg_lo:[0,0,1] neg_hi:[0,0,1]
	v_pk_fma_f32 v[36:37], v[32:33], v[36:37], v[46:47] op_sel_hi:[0,1,1]
	v_mov_b32_e32 v49, v37
	v_pk_mul_f32 v[36:37], v[146:147], v[48:49] op_sel_hi:[0,1]
	v_mul_f32_e32 v46, v35, v39
	v_mul_f32_e32 v48, v34, v39
	v_pk_fma_f32 v[46:47], v[34:35], v[38:39], v[46:47] op_sel_hi:[1,1,0] neg_lo:[0,0,1] neg_hi:[0,0,1]
	v_pk_fma_f32 v[38:39], v[34:35], v[38:39], v[48:49] op_sel:[0,1,0] op_sel_hi:[1,0,0]
	s_nop 0
	v_mov_b32_e32 v47, v39
	v_pk_mul_f32 v[38:39], v[146:147], v[46:47] op_sel_hi:[0,1]
	v_pk_mul_f32 v[46:47], v[28:29], v[40:41] op_sel:[1,1] op_sel_hi:[1,0]
	s_nop 0
	v_pk_fma_f32 v[48:49], v[28:29], v[40:41], v[46:47] neg_lo:[0,0,1] neg_hi:[0,0,1]
	v_pk_fma_f32 v[40:41], v[28:29], v[40:41], v[46:47] op_sel_hi:[0,1,1]
	v_mov_b32_e32 v49, v41
	v_pk_mul_f32 v[40:41], v[146:147], v[48:49] op_sel_hi:[0,1]
	v_mul_f32_e32 v46, v31, v43
	v_mul_f32_e32 v48, v30, v43
	v_pk_fma_f32 v[46:47], v[30:31], v[42:43], v[46:47] op_sel_hi:[1,1,0] neg_lo:[0,0,1] neg_hi:[0,0,1]
	v_pk_fma_f32 v[42:43], v[30:31], v[42:43], v[48:49] op_sel:[0,1,0] op_sel_hi:[1,0,0]
	s_nop 0
	v_mov_b32_e32 v47, v43
	v_pk_mul_f32 v[42:43], v[146:147], v[46:47] op_sel_hi:[0,1]

.LBB0_816:
	v_mov_b64_e32 v[28:29], s[12:13]
	v_mad_i64_i32 v[28:29], s[0:1], v45, s2, v[28:29]
	v_lshl_add_u64 v[28:29], v[124:125], 1, v[28:29]
	v_cvt_pk_bf16_f32 v30, v36, v37
	v_cvt_pk_bf16_f32 v31, v38, v39
	v_cvt_pk_bf16_f32 v32, v40, v41
	v_cvt_pk_bf16_f32 v33, v42, v43
	s_cmp_lt_i32 s19, 2
	s_mov_b64 s[28:29], -1
	global_store_dwordx4 v[28:29], v[30:33], off
	s_cbranch_scc1 .LBB0_822
	s_cmp_gt_i32 s19, 2
	s_cbranch_scc0 .LBB0_819
	s_mov_b64 s[28:29], 0
	v_mov_b32_e32 v34, v208
	v_mov_b32_e32 v35, v209
	v_mov_b32_e32 v36, v210
	v_mov_b32_e32 v37, v211
	v_mov_b32_e32 v30, v204
	v_mov_b32_e32 v31, v205
	v_mov_b32_e32 v32, v206
	v_mov_b32_e32 v33, v207
	v_pk_mul_f32 v[38:39], v[24:25], v[30:31] op_sel:[1,1] op_sel_hi:[1,0]
	s_nop 0
	v_pk_fma_f32 v[40:41], v[24:25], v[30:31], v[38:39] neg_lo:[0,0,1] neg_hi:[0,0,1]
	v_pk_fma_f32 v[30:31], v[24:25], v[30:31], v[38:39] op_sel_hi:[0,1,1]
	v_mov_b32_e32 v41, v31
	v_pk_mul_f32 v[30:31], v[146:147], v[40:41] op_sel_hi:[0,1]
	v_mul_f32_e32 v38, v27, v33
	v_mul_f32_e32 v40, v26, v33
	v_pk_fma_f32 v[38:39], v[26:27], v[32:33], v[38:39] op_sel_hi:[1,1,0] neg_lo:[0,0,1] neg_hi:[0,0,1]
	v_pk_fma_f32 v[32:33], v[26:27], v[32:33], v[40:41] op_sel:[0,1,0] op_sel_hi:[1,0,0]
	s_nop 0
	v_mov_b32_e32 v39, v33
	v_pk_mul_f32 v[32:33], v[146:147], v[38:39] op_sel_hi:[0,1]
	v_pk_mul_f32 v[38:39], v[20:21], v[34:35] op_sel:[1,1] op_sel_hi:[1,0]
	s_nop 0
	v_pk_fma_f32 v[40:41], v[20:21], v[34:35], v[38:39] neg_lo:[0,0,1] neg_hi:[0,0,1]
	v_pk_fma_f32 v[34:35], v[20:21], v[34:35], v[38:39] op_sel_hi:[0,1,1]
	v_mov_b32_e32 v41, v35
	v_pk_mul_f32 v[34:35], v[146:147], v[40:41] op_sel_hi:[0,1]
	v_mul_f32_e32 v38, v23, v37
	v_mul_f32_e32 v40, v22, v37
	v_pk_fma_f32 v[38:39], v[22:23], v[36:37], v[38:39] op_sel_hi:[1,1,0] neg_lo:[0,0,1] neg_hi:[0,0,1]
	v_pk_fma_f32 v[36:37], v[22:23], v[36:37], v[40:41] op_sel:[0,1,0] op_sel_hi:[1,0,0]
	s_nop 0
	v_mov_b32_e32 v39, v37
	v_pk_mul_f32 v[36:37], v[146:147], v[38:39] op_sel_hi:[0,1]

.LBB0_826:
	v_cvt_pk_bf16_f32 v20, v30, v31
	v_cvt_pk_bf16_f32 v21, v32, v33
	v_cvt_pk_bf16_f32 v22, v34, v35
	v_cvt_pk_bf16_f32 v23, v36, v37
	global_store_dwordx4 v[28:29], v[20:23], off offset:256
	s_addk_i32 s4, 0xb0
	s_cmp_lt_i32 s19, 2
	v_add_u32_e32 v29, s4, v160
	v_bitop3_b32 v20, v29, s86, v254 bitop3:0x6c
	v_cmp_gt_i32_e32 vcc, s86, v29
	v_add_u32_e32 v20, 0x100, v20
	s_mov_b64 s[28:29], -1
	v_cndmask_b32_sdwa v20, v20, v29, vcc dst_sel:DWORD dst_unused:UNUSED_PAD src0_sel:DWORD src1_sel:BYTE_0
	v_lshlrev_b32_e32 v28, 5, v20
	s_cbranch_scc1 .LBB0_832
	s_cmp_gt_i32 s19, 2
	s_cbranch_scc0 .LBB0_829
	s_mov_b64 s[28:29], 0
	s_waitcnt vmcnt(6)
	v_mov_b32_e32 v24, v216
	v_mov_b32_e32 v25, v217
	v_mov_b32_e32 v26, v218
	v_mov_b32_e32 v27, v219
	v_mov_b32_e32 v20, v212
	v_mov_b32_e32 v21, v213
	v_mov_b32_e32 v22, v214
	v_mov_b32_e32 v23, v215
	v_pk_mul_f32 v[30:31], v[16:17], v[20:21] op_sel:[1,1] op_sel_hi:[1,0]
	s_nop 0
	v_pk_fma_f32 v[32:33], v[16:17], v[20:21], v[30:31] neg_lo:[0,0,1] neg_hi:[0,0,1]
	v_pk_fma_f32 v[20:21], v[16:17], v[20:21], v[30:31] op_sel_hi:[0,1,1]
	v_mov_b32_e32 v33, v21
	v_pk_mul_f32 v[20:21], v[146:147], v[32:33] op_sel_hi:[0,1]
	v_mul_f32_e32 v30, v19, v23
	v_mul_f32_e32 v32, v18, v23
	v_pk_fma_f32 v[30:31], v[18:19], v[22:23], v[30:31] op_sel_hi:[1,1,0] neg_lo:[0,0,1] neg_hi:[0,0,1]
	v_pk_fma_f32 v[22:23], v[18:19], v[22:23], v[32:33] op_sel:[0,1,0] op_sel_hi:[1,0,0]
	s_nop 0
	v_mov_b32_e32 v31, v23
	v_pk_mul_f32 v[22:23], v[146:147], v[30:31] op_sel_hi:[0,1]
	v_pk_mul_f32 v[30:31], v[12:13], v[24:25] op_sel:[1,1] op_sel_hi:[1,0]
	s_nop 0
	v_pk_fma_f32 v[32:33], v[12:13], v[24:25], v[30:31] neg_lo:[0,0,1] neg_hi:[0,0,1]
	v_pk_fma_f32 v[24:25], v[12:13], v[24:25], v[30:31] op_sel_hi:[0,1,1]
	v_mov_b32_e32 v33, v25
	v_pk_mul_f32 v[24:25], v[146:147], v[32:33] op_sel_hi:[0,1]
	v_mul_f32_e32 v30, v15, v27
	v_mul_f32_e32 v32, v14, v27
	v_pk_fma_f32 v[30:31], v[14:15], v[26:27], v[30:31] op_sel_hi:[1,1,0] neg_lo:[0,0,1] neg_hi:[0,0,1]
	v_pk_fma_f32 v[26:27], v[14:15], v[26:27], v[32:33] op_sel:[0,1,0] op_sel_hi:[1,0,0]
	s_nop 0
	v_mov_b32_e32 v31, v27
	v_pk_mul_f32 v[26:27], v[146:147], v[30:31] op_sel_hi:[0,1]

.LBB0_836:
	v_mov_b64_e32 v[12:13], s[12:13]
	v_mad_i64_i32 v[12:13], s[0:1], v29, s2, v[12:13]
	v_lshl_add_u64 v[12:13], v[124:125], 1, v[12:13]
	v_cvt_pk_bf16_f32 v14, v20, v21
	v_cvt_pk_bf16_f32 v15, v22, v23
	v_cvt_pk_bf16_f32 v16, v24, v25
	v_cvt_pk_bf16_f32 v17, v26, v27
	s_cmp_lt_i32 s19, 2
	s_mov_b64 s[28:29], -1
	global_store_dwordx4 v[12:13], v[14:17], off
	s_cbranch_scc1 .LBB0_842
	s_cmp_gt_i32 s19, 2
	s_cbranch_scc0 .LBB0_839
	s_mov_b64 s[28:29], 0
	v_mov_b32_e32 v20, v216
	v_mov_b32_e32 v21, v217
	v_mov_b32_e32 v22, v218
	v_mov_b32_e32 v23, v219
	v_mov_b32_e32 v14, v212
	v_mov_b32_e32 v15, v213
	v_mov_b32_e32 v16, v214
	v_mov_b32_e32 v17, v215
	v_pk_mul_f32 v[18:19], v[8:9], v[14:15] op_sel:[1,1] op_sel_hi:[1,0]
	s_nop 0
	v_pk_fma_f32 v[24:25], v[8:9], v[14:15], v[18:19] neg_lo:[0,0,1] neg_hi:[0,0,1]
	v_pk_fma_f32 v[14:15], v[8:9], v[14:15], v[18:19] op_sel_hi:[0,1,1]
	v_mov_b32_e32 v25, v15
	v_pk_mul_f32 v[14:15], v[146:147], v[24:25] op_sel_hi:[0,1]
	v_mul_f32_e32 v18, v11, v17
	v_mul_f32_e32 v24, v10, v17
	v_pk_fma_f32 v[18:19], v[10:11], v[16:17], v[18:19] op_sel_hi:[1,1,0] neg_lo:[0,0,1] neg_hi:[0,0,1]
	v_pk_fma_f32 v[16:17], v[10:11], v[16:17], v[24:25] op_sel:[0,1,0] op_sel_hi:[1,0,0]
	s_nop 0
	v_mov_b32_e32 v19, v17
	v_pk_mul_f32 v[16:17], v[4:5], v[20:21] op_sel:[1,1] op_sel_hi:[1,0]
	v_pk_mul_f32 v[18:19], v[146:147], v[18:19] op_sel_hi:[0,1]
	v_pk_fma_f32 v[24:25], v[4:5], v[20:21], v[16:17] neg_lo:[0,0,1] neg_hi:[0,0,1]
	v_pk_fma_f32 v[16:17], v[4:5], v[20:21], v[16:17] op_sel_hi:[0,1,1]
	v_mov_b32_e32 v25, v17
	v_pk_mul_f32 v[16:17], v[146:147], v[24:25] op_sel_hi:[0,1]
	v_mul_f32_e32 v20, v7, v23
	v_mul_f32_e32 v24, v6, v23
	v_pk_fma_f32 v[20:21], v[6:7], v[22:23], v[20:21] op_sel_hi:[1,1,0] neg_lo:[0,0,1] neg_hi:[0,0,1]
	v_pk_fma_f32 v[22:23], v[6:7], v[22:23], v[24:25] op_sel:[0,1,0] op_sel_hi:[1,0,0]
	s_nop 0
	v_mov_b32_e32 v21, v23
	v_pk_mul_f32 v[20:21], v[146:147], v[20:21] op_sel_hi:[0,1]
